# scan: decay factor hoisted out of the item loop (computed on the first trip only when stride keeps head/dir bits)
# baseline (speedup 1.0000x reference)
; __device__ __forceinline__ void ret_gammas(const Args& a, int l, int h, float& lgf2, float& lgb2) {
;     const float xf = a.in[8][(l * 2 + 0) * 4 + h], xb = a.in[8][(l * 2 + 1) * 4 + h];
;     lgf2 = -log1pf(expf(-xf)) * LOG2E; lgb2 = -log1pf(expf(-xb)) * LOG2E;
; }
; __device__ __forceinline__ void phase_scan(const Args& a, unsigned char* ws, bf16* STB, int l, int vcu, int G, int tid, int z) {
;     bf16* ST = STB;
;     const int gt = vcu * 512 + tid, NT = G * 512;
;     for (int it = gt; it < 192 * 2 * 2048; it += NT) {
;         const int grp = it & 2047, dir = (it >> 11) & 1, bh = it >> 12, h = bh & 3;
;         float lgf2, lgb2; ret_gammas(a, l, h, lgf2, lgb2);
;         const float g = __builtin_amdgcn_exp2f(128.f * (dir ? lgb2 : lgf2));
;         bf16* base = ST + ((size_t)(bh * 16) * 2 + dir) * 16384 + grp * 8;
;         u32x4 kv[16];
;         const size_t cst = (size_t)(32768 + z);
; #pragma unroll
;         for (int n = 0; n < 16; ++n) kv[n] = *(const u32x4*)(base + (size_t)n * cst);
.LBB0_562:
	v_lshl_add_u32 v74, s3, 9, v0
	s_mov_b32 s0, 0xc0000
	v_cmp_gt_i32_e32 vcc, s0, v74
	s_and_saveexec_b64 s[4:5], vcc
	s_cbranch_execz .LBB0_565
	s_load_dwordx2 s[8:9], s[78:79], 0xa8
	s_load_dwordx2 s[6:7], s[78:79], 0x40
	s_ashr_i32 s0, s2, 31
	v_lshlrev_b32_e32 v0, 3, v0
	v_mov_b32_e32 v65, 0
	s_waitcnt lgkmcnt(0)
	s_add_u32 s8, s8, s2
	s_addc_u32 s9, s9, s0
	s_add_i32 s10, s2, 0x8000
	s_ashr_i32 s11, s10, 31
	s_lshl_b32 s0, s1, 9
	s_lshl_b64 s[12:13], s[10:11], 1
	v_lshl_add_u32 v75, s3, 12, v0
	s_lshl_b32 s1, s1, 12
	s_mov_b64 s[14:15], 0
	s_mov_b32 s16, 0xbfb8aa3b
	s_mov_b32 s17, 0x42ce8ed0
	s_mov_b32 s18, 0xc2b17218
	s_mov_b32 s19, 0x7f800000
	v_mov_b32_e32 v76, 0x7f800000
	s_mov_b32 s20, 0x3f2aaaab
	v_mov_b32_e32 v77, 0x3ecc95a3
	s_mov_b32 s21, 0x3f317218
	s_mov_b32 s98, 1
	s_and_b32 s99, s0, 0x3fff
	s_mov_b32 s22, 0x33800000
	v_mov_b32_e32 v80, v65
	v_mov_b32_e32 v81, v65
	v_mov_b32_e32 v82, v65
	v_mov_b32_e32 v83, v65
	s_mov_b32 s23, 0xbffff
	v_mov_b32_e32 v66, 0x3f317218
.LBB0_564:
	v_ashrrev_i32_e32 v1, 12, v74
	v_lshlrev_b32_e32 v3, 2, v1
	v_and_b32_e32 v3, 12, v3
	global_load_dword v67, v3, s[6:7]
	global_load_dword v79, v3, s[6:7] offset:16
	v_lshlrev_b32_e32 v4, 4, v1
	v_ashrrev_i32_e32 v5, 31, v4
	v_bfe_u32 v78, v74, 11, 1
	v_lshlrev_b64 v[4:5], 16, v[4:5]
	v_and_b32_e32 v2, 0x3ff8, v75
	v_lshlrev_b32_e32 v0, 15, v78
	v_lshl_add_u64 v[4:5], s[8:9], 0, v[4:5]
	v_lshl_add_u32 v0, v2, 1, v0
	v_add_co_u32_e32 v72, vcc, v4, v0
	v_addc_co_u32_e32 v73, vcc, 0, v5, vcc
	v_lshl_add_u64 v[4:5], s[10:11], 1, v[72:73]
	v_lshl_add_u64 v[12:13], v[4:5], 0, s[12:13]
	v_bfe_i32 v0, v74, 11, 1
	v_lshl_add_u64 v[14:15], v[12:13], 0, s[12:13]
	v_and_b32_e32 v0, 15, v0
	v_add_u32_e32 v6, 7, v78
	v_sub_u32_e32 v8, 8, v78
	v_lshl_add_u64 v[16:17], v[14:15], 0, s[12:13]
	v_mad_i64_i32 v[0:1], s[2:3], v0, s10, 0
	v_mad_i64_i32 v[6:7], s[2:3], v6, s10, 0
	v_mad_i64_i32 v[8:9], s[2:3], v8, s10, 0
	v_lshl_add_u64 v[18:19], v[16:17], 0, s[12:13]
	v_lshl_add_u64 v[84:85], v[0:1], 1, v[72:73]
	v_lshl_add_u64 v[70:71], v[6:7], 1, v[72:73]
	v_lshl_add_u64 v[68:69], v[8:9], 1, v[72:73]
	global_load_dwordx4 v[56:59], v[72:73], off
	global_load_dwordx4 v[0:3], v[4:5], off
	s_nop 0
	global_load_dwordx4 v[4:7], v[12:13], off
	global_load_dwordx4 v[8:11], v[14:15], off
	s_nop 0
	global_load_dwordx4 v[12:15], v[16:17], off
	global_load_dwordx4 v[20:23], v[18:19], off
	v_lshl_add_u64 v[16:17], v[18:19], 0, s[12:13]
	global_load_dwordx4 v[32:35], v[16:17], off
	v_lshl_add_u64 v[16:17], v[16:17], 0, s[12:13]
	global_load_dwordx4 v[48:51], v[16:17], off
	v_lshl_add_u64 v[16:17], v[16:17], 0, s[12:13]
	global_load_dwordx4 v[52:55], v[16:17], off
	v_lshl_add_u64 v[16:17], v[16:17], 0, s[12:13]
	global_load_dwordx4 v[44:47], v[16:17], off
	v_lshl_add_u64 v[16:17], v[16:17], 0, s[12:13]
	global_load_dwordx4 v[40:43], v[16:17], off
	v_lshl_add_u64 v[16:17], v[16:17], 0, s[12:13]
	global_load_dwordx4 v[36:39], v[16:17], off
	v_lshl_add_u64 v[16:17], v[16:17], 0, s[12:13]
	global_load_dwordx4 v[28:31], v[16:17], off
	v_lshl_add_u64 v[16:17], v[16:17], 0, s[12:13]
	v_lshl_add_u64 v[60:61], v[16:17], 0, s[12:13]
	global_load_dwordx4 v[24:27], v[16:17], off
	v_add_u32_e32 v74, s0, v74
	global_load_dwordx4 v[16:19], v[60:61], off
	v_lshl_add_u64 v[60:61], v[60:61], 0, s[12:13]
	global_load_dwordx4 v[60:63], v[60:61], off
	v_cmp_lt_i32_e32 vcc, s23, v74
	global_store_dwordx4 v[84:85], v[80:83], off
	s_or_b64 s[14:15], vcc, s[14:15]
	v_add_u32_e32 v75, s1, v75
	s_cmp_eq_u32 s98, 0
	s_cbranch_scc1 .Lscan_gskip_0
	s_waitcnt vmcnt(17)
	v_mul_f32_e32 v64, 0xbfb8aa3b, v67
	v_mul_f32_e32 v84, 0xbfb8aa3b, v79
	v_fma_f32 v85, v67, s16, -v64
	v_rndne_f32_e32 v86, v64
	v_fma_f32 v87, v79, s16, -v84
	v_rndne_f32_e32 v88, v84
	v_fmac_f32_e32 v85, 0xb2a5705f, v67
	v_sub_f32_e32 v64, v64, v86
	v_fmac_f32_e32 v87, 0xb2a5705f, v79
	v_sub_f32_e32 v84, v84, v88
	v_add_f32_e32 v64, v64, v85
	v_cvt_i32_f32_e32 v86, v86
	v_add_f32_e32 v84, v84, v87
	v_exp_f32_e32 v64, v64
	v_cvt_i32_f32_e32 v88, v88
	v_exp_f32_e32 v84, v84
	v_cmp_nlt_f32_e64 s[2:3], s17, v67
	v_ldexp_f32 v64, v64, v86
	v_cmp_nlt_f32_e32 vcc, s17, v79
	v_ldexp_f32 v84, v84, v88
	v_cndmask_b32_e64 v64, 0, v64, s[2:3]
	v_cmp_ngt_f32_e64 s[2:3], s18, v67
	v_cndmask_b32_e32 v84, 0, v84, vcc
	v_cmp_ngt_f32_e32 vcc, s18, v79
	v_cndmask_b32_e64 v64, v76, v64, s[2:3]
	v_add_f32_e32 v67, 1.0, v64
	v_cndmask_b32_e32 v79, v76, v84, vcc
	v_add_f32_e32 v88, 1.0, v79
	v_add_f32_e32 v89, -1.0, v67
	v_frexp_mant_f32_e32 v90, v67
	v_cvt_f64_f32_e32 v[84:85], v67
	v_add_f32_e32 v91, -1.0, v88
	v_frexp_mant_f32_e32 v92, v88
	v_cvt_f64_f32_e32 v[86:87], v88
	v_sub_f32_e32 v93, v89, v67
	v_frexp_exp_i32_f64_e32 v84, v[84:85]
	v_cmp_gt_f32_e32 vcc, s20, v90
	v_sub_f32_e32 v89, v64, v89
	v_sub_f32_e32 v85, v91, v88
	v_frexp_exp_i32_f64_e32 v86, v[86:87]
	v_cmp_gt_f32_e64 s[2:3], s20, v92
	v_add_f32_e32 v87, 1.0, v93
	v_subbrev_co_u32_e32 v84, vcc, 0, v84, vcc
	v_sub_f32_e32 v90, v79, v91
	v_add_f32_e32 v85, 1.0, v85
	v_subbrev_co_u32_e64 v86, vcc, 0, v86, s[2:3]
	v_add_f32_e32 v87, v89, v87
	v_sub_u32_e32 v89, 0, v84
	v_add_f32_e32 v85, v90, v85
	v_sub_u32_e32 v90, 0, v86
	v_ldexp_f32 v67, v67, v89
	v_ldexp_f32 v88, v88, v90
	v_ldexp_f32 v85, v85, v90
	v_add_f32_e32 v90, -1.0, v67
	v_add_f32_e32 v92, 1.0, v67
	v_ldexp_f32 v87, v87, v89
	v_add_f32_e32 v93, -1.0, v88
	v_add_f32_e32 v94, 1.0, v88
	v_add_f32_e32 v89, 1.0, v90
	v_add_f32_e32 v91, -1.0, v92
	v_add_f32_e32 v95, 1.0, v93
	v_add_f32_e32 v96, -1.0, v94
	v_sub_f32_e32 v89, v67, v89
	v_sub_f32_e32 v67, v67, v91
	v_sub_f32_e32 v91, v88, v95
	v_sub_f32_e32 v88, v88, v96
	v_add_f32_e32 v67, v87, v67
; __device__ __forceinline__ void ret_gammas(const Args& a, int l, int h, float& lgf2, float& lgb2) {
;     const float xf = a.in[8][(l * 2 + 0) * 4 + h], xb = a.in[8][(l * 2 + 1) * 4 + h];
;     lgf2 = -log1pf(expf(-xf)) * LOG2E; lgb2 = -log1pf(expf(-xb)) * LOG2E;
; __device__ __forceinline__ void phase_scan(const Args& a, unsigned char* ws, bf16* STB, int l, int vcu, int G, int tid, int z) {
;     ...
;         const float g = __builtin_amdgcn_exp2f(128.f * (dir ? lgb2 : lgf2));
	v_add_f32_e32 v95, v87, v89
	v_add_f32_e32 v87, v85, v91
	v_add_f32_e32 v85, v85, v88
	v_add_f32_e32 v100, v92, v67
	v_add_f32_e32 v101, v94, v85
	v_rcp_f32_e32 v102, v100
	v_rcp_f32_e32 v103, v101
	v_add_f32_e32 v89, v90, v95
	v_add_f32_e32 v91, v93, v87
	v_sub_f32_e32 v88, v92, v100
	v_sub_f32_e32 v92, v94, v101
	v_mul_f32_e32 v105, v89, v102
	v_add_f32_e32 v85, v85, v92
	v_mul_f32_e32 v106, v91, v103
	v_mul_f32_e32 v92, v100, v105
	v_add_f32_e32 v67, v67, v88
	v_mul_f32_e32 v94, v101, v106
	v_fma_f32 v96, v105, v100, -v92
	v_fma_f32 v98, v106, v101, -v94
	v_fmac_f32_e32 v96, v105, v67
	v_sub_f32_e32 v90, v90, v89
	v_sub_f32_e32 v93, v93, v91
	v_fmac_f32_e32 v98, v106, v85
	v_add_f32_e32 v88, v92, v96
	v_add_f32_e32 v104, v95, v90
	v_add_f32_e32 v87, v87, v93
	v_add_f32_e32 v90, v94, v98
	v_sub_f32_e32 v93, v89, v88
	v_mov_b32_e32 v97, v88
	v_sub_f32_e32 v95, v91, v90
	v_pk_add_f32 v[88:89], v[88:89], v[92:93] neg_lo:[0,1] neg_hi:[0,1]
	v_mov_b32_e32 v99, v90
	v_pk_add_f32 v[90:91], v[90:91], v[94:95] neg_lo:[0,1] neg_hi:[0,1]
	v_pk_add_f32 v[88:89], v[88:89], v[96:97] neg_lo:[0,1] neg_hi:[0,1]
	v_pk_add_f32 v[90:91], v[90:91], v[98:99] neg_lo:[0,1] neg_hi:[0,1]
	v_add_f32_e32 v89, v104, v89
	v_add_f32_e32 v87, v87, v91
	v_add_f32_e32 v88, v88, v89
	v_add_f32_e32 v87, v90, v87
	v_add_f32_e32 v89, v93, v88
	v_add_f32_e32 v91, v95, v87
	v_mul_f32_e32 v90, v102, v89
	v_mul_f32_e32 v97, v103, v91
	v_mul_f32_e32 v92, v100, v90
	v_sub_f32_e32 v93, v93, v89
	v_add_f32_e32 v107, v105, v90
	v_mul_f32_e32 v94, v101, v97
	v_fma_f32 v96, v90, v100, -v92
	v_add_f32_e32 v104, v88, v93
	v_add_f32_e32 v108, v106, v97
	v_sub_f32_e32 v88, v107, v105
	v_fma_f32 v98, v97, v101, -v94
	v_fmac_f32_e32 v96, v90, v67
	v_sub_f32_e32 v93, v108, v106
	v_sub_f32_e32 v67, v90, v88
	v_fmac_f32_e32 v98, v97, v85
	v_add_f32_e32 v88, v92, v96
	v_sub_f32_e32 v95, v95, v91
	v_sub_f32_e32 v85, v97, v93
	v_add_f32_e32 v90, v94, v98
	v_sub_f32_e32 v93, v89, v88
	v_add_f32_e32 v87, v87, v95
	v_mov_b32_e32 v97, v88
	v_sub_f32_e32 v95, v91, v90
	v_pk_add_f32 v[88:89], v[88:89], v[92:93] neg_lo:[0,1] neg_hi:[0,1]
	v_mov_b32_e32 v99, v90
	v_pk_add_f32 v[90:91], v[90:91], v[94:95] neg_lo:[0,1] neg_hi:[0,1]
	v_pk_add_f32 v[88:89], v[88:89], v[96:97] neg_lo:[0,1] neg_hi:[0,1]
	v_pk_add_f32 v[90:91], v[90:91], v[98:99] neg_lo:[0,1] neg_hi:[0,1]
	v_add_f32_e32 v89, v104, v89
	v_add_f32_e32 v87, v87, v91
	v_add_f32_e32 v88, v88, v89
	v_add_f32_e32 v87, v90, v87
	v_add_f32_e32 v88, v93, v88
	v_add_f32_e32 v87, v95, v87
	v_mul_f32_e32 v88, v102, v88
	v_mul_f32_e32 v87, v103, v87
	v_add_f32_e32 v67, v67, v88
	v_cvt_f32_i32_e32 v84, v84
	v_add_f32_e32 v87, v85, v87
	v_add_f32_e32 v85, v107, v67
	v_cvt_f32_i32_e32 v86, v86
	v_add_f32_e32 v88, v108, v87
	v_mul_f32_e32 v90, v85, v85
	v_sub_f32_e32 v92, v85, v107
	v_mul_f32_e32 v94, v88, v88
	v_sub_f32_e32 v93, v88, v108
	v_fmamk_f32 v95, v90, 0x3e9b6dac, v77
	v_ldexp_f32 v89, v85, 1
	v_sub_f32_e32 v92, v67, v92
	v_mul_f32_e32 v85, v85, v90
	v_fmamk_f32 v96, v94, 0x3e9b6dac, v77
	v_sub_f32_e32 v93, v87, v93
	v_fmaak_f32 v67, v90, v95, 0x3f2aaada
	v_mul_f32_e32 v87, v88, v94
	v_ldexp_f32 v95, v92, 1
	v_ldexp_f32 v104, v93, 1
	v_pk_mul_f32 v[92:93], v[84:85], v[66:67]
	v_fmaak_f32 v67, v94, v96, 0x3f2aaada
	v_ldexp_f32 v91, v88, 1
	v_fma_f32 v88, v84, s21, -v92
	v_pk_mul_f32 v[96:97], v[86:87], v[66:67]
	v_fmac_f32_e32 v88, 0xb102e308, v84
	v_fma_f32 v90, v86, s21, -v96
	v_pk_add_f32 v[98:99], v[92:93], v[88:89]
	v_fmac_f32_e32 v90, 0xb102e308, v86
	v_sub_f32_e32 v67, v99, v89
	v_pk_add_f32 v[102:103], v[96:97], v[90:91]
	v_sub_f32_e32 v67, v93, v67
	v_sub_f32_e32 v85, v103, v91
	v_mov_b32_e32 v94, v92
	v_add_f32_e32 v95, v95, v67
	v_sub_f32_e32 v67, v97, v85
	v_mov_b32_e32 v84, v96
	v_pk_add_f32 v[86:87], v[98:99], v[92:93] neg_lo:[0,1] neg_hi:[0,1]
	v_pk_add_f32 v[92:93], v[102:103], v[96:97] neg_lo:[0,1] neg_hi:[0,1]
	v_pk_add_f32 v[96:97], v[98:99], v[94:95]
	v_add_f32_e32 v85, v104, v67
	v_mov_b32_e32 v89, v98
	v_mov_b32_e32 v87, v97
	v_pk_add_f32 v[106:107], v[102:103], v[84:85]
	v_mov_b32_e32 v91, v102
	v_mov_b32_e32 v104, v85
	v_pk_add_f32 v[84:85], v[88:89], v[86:87] neg_lo:[0,1] neg_hi:[0,1]
	v_pk_add_f32 v[86:87], v[88:89], v[86:87]
	v_mov_b32_e32 v93, v107
	v_pk_add_f32 v[108:109], v[86:87], v[98:99] op_sel:[1,0] op_sel_hi:[0,1] neg_lo:[0,1] neg_hi:[0,1]
	v_pk_add_f32 v[110:111], v[90:91], v[92:93] neg_lo:[0,1] neg_hi:[0,1]
	v_pk_add_f32 v[90:91], v[90:91], v[92:93]
	v_mov_b32_e32 v101, v98
	v_mov_b32_e32 v100, v95
	v_mov_b32_e32 v94, v97
	v_mov_b32_e32 v95, v87
	v_pk_add_f32 v[92:93], v[96:97], v[108:109] op_sel_hi:[1,0] neg_lo:[0,1] neg_hi:[0,1]
	v_pk_mov_b32 v[96:97], v[98:99], v[108:109] op_sel:[1,0]
	v_pk_add_f32 v[98:99], v[90:91], v[102:103] op_sel:[1,0] op_sel_hi:[0,1] neg_lo:[0,1] neg_hi:[0,1]
	v_mov_b32_e32 v88, v107
	v_mov_b32_e32 v89, v91
	v_pk_add_f32 v[94:95], v[94:95], v[96:97] neg_lo:[0,1] neg_hi:[0,1]
	v_pk_add_f32 v[96:97], v[106:107], v[98:99] op_sel_hi:[1,0] neg_lo:[0,1] neg_hi:[0,1]
	v_pk_mov_b32 v[98:99], v[102:103], v[98:99] op_sel:[1,0]
	v_mov_b32_e32 v105, v102
	v_mov_b32_e32 v92, v84
	v_pk_add_f32 v[94:95], v[100:101], v[94:95] neg_lo:[0,1] neg_hi:[0,1]
	v_pk_add_f32 v[88:89], v[88:89], v[98:99] neg_lo:[0,1] neg_hi:[0,1]
	v_mov_b32_e32 v96, v110
	v_pk_add_f32 v[92:93], v[92:93], v[94:95]
	v_pk_add_f32 v[88:89], v[104:105], v[88:89] neg_lo:[0,1] neg_hi:[0,1]
	v_pk_add_f32 v[98:99], v[92:93], v[92:93] op_sel:[0,1] op_sel_hi:[1,0]
	v_pk_add_f32 v[96:97], v[96:97], v[88:89]
	v_mov_b32_e32 v85, v87
	v_pk_add_f32 v[86:87], v[86:87], v[98:99] op_sel:[1,0] op_sel_hi:[0,1]
	v_mov_b32_e32 v95, v98
	v_pk_add_f32 v[98:99], v[96:97], v[96:97] op_sel:[0,1] op_sel_hi:[1,0]
	v_mov_b32_e32 v111, v91
	v_mov_b32_e32 v93, v86
	v_pk_add_f32 v[90:91], v[90:91], v[98:99] op_sel:[1,0] op_sel_hi:[0,1]
	v_mov_b32_e32 v89, v98
	v_pk_add_f32 v[98:99], v[92:93], v[84:85] neg_lo:[0,1] neg_hi:[0,1]
	v_mov_b32_e32 v97, v90
	v_sub_f32_e32 v67, v92, v98
	v_pk_add_f32 v[92:93], v[96:97], v[110:111] neg_lo:[0,1] neg_hi:[0,1]
	v_pk_add_f32 v[94:95], v[94:95], v[98:99] neg_lo:[0,1] neg_hi:[0,1]
	v_sub_f32_e32 v67, v84, v67
	v_sub_f32_e32 v87, v96, v92
	v_pk_add_f32 v[84:85], v[88:89], v[92:93] neg_lo:[0,1] neg_hi:[0,1]
	v_add_f32_e32 v67, v94, v67
	v_sub_f32_e32 v87, v110, v87
	v_add_f32_e32 v67, v67, v95
	v_add_f32_e32 v84, v84, v87
	v_add_f32_e32 v67, v86, v67
	v_add_f32_e32 v84, v84, v85
	v_cmp_neq_f32_e32 vcc, s19, v64
	v_add_f32_e32 v84, v90, v84
	v_cmp_lt_f32_e64 s[2:3], |v64|, s22
	v_cndmask_b32_e32 v67, v76, v67, vcc
	v_cmp_neq_f32_e32 vcc, s19, v79
	v_cndmask_b32_e64 v64, v67, v64, s[2:3]
	s_nop 0
	v_cndmask_b32_e32 v67, v76, v84, vcc
	v_cmp_lt_f32_e64 vcc, |v79|, s22
	s_nop 1
	v_cndmask_b32_e32 v67, v67, v79, vcc
	v_cmp_eq_u32_e32 vcc, 0, v78
	s_nop 1
	v_cndmask_b32_e32 v64, v67, v64, vcc
	v_mul_f32_e32 v64, 0xbfb8aa3b, v64
	v_mul_f32_e32 v64, 0x43000000, v64
	v_exp_f32_e32 v64, v64
	s_mov_b32 s98, s99
; __device__ __forceinline__ unsigned pkbf(float lo, float hi) { typedef __bf16 bf2_t __attribute__((ext_vector_type(2))); f32x2 v = {lo, hi}; bf2_t b = __builtin_convertvector(v, bf2_t); return __builtin_bit_cast(unsigned, b); }
; __device__ __forceinline__ void phase_scan(const Args& a, unsigned char* ws, bf16* STB, int l, int vcu, int G, int tid, int z) {
;     ...
;         for (int n = 0; n < 16; ++n) kv[n] = *(const u32x4*)(base + (size_t)n * cst);
;         float c[8];
; #pragma unroll
;         for (int e = 0; e < 8; ++e) c[e] = 0.f;
; #pragma unroll
;         for (int i = 0; i < 16; ++i) {
;             const int n = dir ? 15 - i : i;
;             u32x4 w; w.x = pkbf(c[0], c[1]); w.y = pkbf(c[2], c[3]); w.z = pkbf(c[4], c[5]); w.w = pkbf(c[6], c[7]);
;             *(u32x4*)(base + (size_t)n * cst) = w;
; #pragma unroll
;             for (int e = 0; e < 4; ++e) { c[2 * e] = bflo(kv[n][e]) + g * c[2 * e]; c[2 * e + 1] = bfhi(kv[n][e]) + g * c[2 * e + 1]; }
.Lscan_gskip_0:
	v_cmp_eq_u32_e32 vcc, 0, v78
	s_waitcnt vmcnt(0)
	s_nop 1
	v_cndmask_b32_e32 v59, v63, v59, vcc
	v_cndmask_b32_e32 v58, v62, v58, vcc
	v_cndmask_b32_e32 v57, v61, v57, vcc
	v_cndmask_b32_e32 v56, v60, v56, vcc
	v_cndmask_b32_e64 v60, 14, 1, vcc
	v_cndmask_b32_e32 v61, v19, v3, vcc
	v_cndmask_b32_e32 v62, v18, v2, vcc
	v_cndmask_b32_e32 v63, v17, v1, vcc
	v_cndmask_b32_e64 v78, 13, 2, vcc
	v_cndmask_b32_e32 v79, v27, v7, vcc
	v_cndmask_b32_e32 v84, v26, v6, vcc
	v_cndmask_b32_e32 v85, v25, v5, vcc
	v_cndmask_b32_e32 v86, v24, v4, vcc
	v_cndmask_b32_e64 v87, 12, 3, vcc
	v_cndmask_b32_e32 v88, v31, v11, vcc
	v_cndmask_b32_e32 v89, v30, v10, vcc
	v_cndmask_b32_e32 v90, v29, v9, vcc
	v_cndmask_b32_e32 v91, v28, v8, vcc
	v_cndmask_b32_e64 v92, 11, 4, vcc
	v_cndmask_b32_e32 v93, v39, v15, vcc
	v_cndmask_b32_e32 v96, v36, v12, vcc
	v_cndmask_b32_e64 v97, 10, 5, vcc
	v_cndmask_b32_e32 v98, v43, v23, vcc
	v_cndmask_b32_e32 v99, v42, v22, vcc
	v_cndmask_b32_e32 v100, v41, v21, vcc
	v_cndmask_b32_e32 v101, v40, v20, vcc
	v_cndmask_b32_e64 v102, 9, 6, vcc
	v_cndmask_b32_e32 v103, v47, v35, vcc
	v_cndmask_b32_e32 v104, v46, v34, vcc
	v_cndmask_b32_e32 v105, v45, v33, vcc
	v_cndmask_b32_e32 v106, v44, v32, vcc
	v_cndmask_b32_e32 v107, v55, v51, vcc
	v_cndmask_b32_e32 v108, v54, v50, vcc
	v_cndmask_b32_e32 v109, v53, v49, vcc
	v_cndmask_b32_e32 v110, v52, v48, vcc
	v_cndmask_b32_e32 v111, v51, v55, vcc
	v_cndmask_b32_e32 v112, v50, v54, vcc
	v_cndmask_b32_e32 v113, v49, v53, vcc
	v_cndmask_b32_e64 v115, 6, 9, vcc
	v_cndmask_b32_e32 v116, v35, v47, vcc
	v_cndmask_b32_e32 v117, v34, v46, vcc
	v_cndmask_b32_e32 v118, v33, v45, vcc
	v_cndmask_b32_e32 v119, v32, v44, vcc
	v_cndmask_b32_e64 v120, 5, 10, vcc
	v_cndmask_b32_e32 v122, v22, v42, vcc
	v_cndmask_b32_e32 v123, v21, v41, vcc
	v_cndmask_b32_e64 v125, 4, 11, vcc
	v_cndmask_b32_e64 v132, 3, 12, vcc
	v_cndmask_b32_e64 v142, 2, 13, vcc
	v_cndmask_b32_e64 v152, 1, 14, vcc
	v_cndmask_b32_e64 v162, 0, 15, vcc
	v_cndmask_b32_e32 v67, v16, v0, vcc
	v_cndmask_b32_e32 v94, v38, v14, vcc
	v_cndmask_b32_e32 v95, v37, v13, vcc
	v_cndmask_b32_e32 v114, v48, v52, vcc
	v_cndmask_b32_e32 v121, v23, v43, vcc
	v_cndmask_b32_e32 v124, v20, v40, vcc
	v_cndmask_b32_e32 v131, v15, v39, vcc
	v_cndmask_b32_e32 v129, v14, v38, vcc
	v_cndmask_b32_e32 v127, v13, v37, vcc
	v_cndmask_b32_e32 v126, v12, v36, vcc
	v_cndmask_b32_e32 v141, v11, v31, vcc
	v_cndmask_b32_e32 v139, v10, v30, vcc
	v_cndmask_b32_e32 v137, v9, v29, vcc
	v_cndmask_b32_e32 v135, v8, v28, vcc
	v_cndmask_b32_e32 v151, v7, v27, vcc
	v_cndmask_b32_e32 v149, v6, v26, vcc
	v_cndmask_b32_e32 v147, v5, v25, vcc
	v_cndmask_b32_e32 v145, v4, v24, vcc
	v_cndmask_b32_e32 v161, v3, v19, vcc
	v_cndmask_b32_e32 v159, v2, v18, vcc
	v_cndmask_b32_e32 v157, v1, v17, vcc
	v_cndmask_b32_e32 v155, v0, v16, vcc
	v_lshlrev_b32_e32 v0, 16, v56
	v_and_b32_e32 v1, 0xffff0000, v56
	v_lshlrev_b32_e32 v2, 16, v57
	v_and_b32_e32 v3, 0xffff0000, v57
	v_lshlrev_b32_e32 v4, 16, v58
	v_and_b32_e32 v5, 0xffff0000, v58
	v_lshlrev_b32_e32 v6, 16, v59
	v_and_b32_e32 v7, 0xffff0000, v59
	v_mad_i64_i32 v[8:9], s[2:3], v60, s10, 0
	v_lshlrev_b32_e32 v12, 16, v63
	v_and_b32_e32 v13, 0xffff0000, v63
	v_lshlrev_b32_e32 v14, 16, v62
	v_and_b32_e32 v15, 0xffff0000, v62
	v_lshlrev_b32_e32 v16, 16, v61
	v_and_b32_e32 v17, 0xffff0000, v61
	v_mad_i64_i32 v[18:19], s[2:3], v78, s10, 0
	v_lshlrev_b32_e32 v20, 16, v86
	v_and_b32_e32 v21, 0xffff0000, v86
	v_lshlrev_b32_e32 v22, 16, v85
	v_and_b32_e32 v23, 0xffff0000, v85
	v_lshlrev_b32_e32 v24, 16, v84
	v_and_b32_e32 v25, 0xffff0000, v84
	v_lshlrev_b32_e32 v26, 16, v79
	v_and_b32_e32 v27, 0xffff0000, v79
	v_mad_i64_i32 v[28:29], s[2:3], v87, s10, 0
	v_lshlrev_b32_e32 v30, 16, v91
	v_and_b32_e32 v31, 0xffff0000, v91
	v_lshlrev_b32_e32 v32, 16, v90
	v_and_b32_e32 v33, 0xffff0000, v90
	v_lshlrev_b32_e32 v34, 16, v89
	v_and_b32_e32 v35, 0xffff0000, v89
	v_lshlrev_b32_e32 v36, 16, v88
	v_and_b32_e32 v37, 0xffff0000, v88
	v_mad_i64_i32 v[38:39], s[2:3], v92, s10, 0
	v_lshlrev_b32_e32 v40, 16, v96
	v_and_b32_e32 v41, 0xffff0000, v96
	v_lshlrev_b32_e32 v46, 16, v93
	v_and_b32_e32 v47, 0xffff0000, v93
	v_mad_i64_i32 v[48:49], s[2:3], v97, s10, 0
	v_lshlrev_b32_e32 v50, 16, v101
	v_and_b32_e32 v51, 0xffff0000, v101
	v_lshlrev_b32_e32 v52, 16, v100
	v_and_b32_e32 v53, 0xffff0000, v100
	v_lshlrev_b32_e32 v54, 16, v99
	v_and_b32_e32 v55, 0xffff0000, v99
	v_lshlrev_b32_e32 v56, 16, v98
	v_and_b32_e32 v57, 0xffff0000, v98
	v_mad_i64_i32 v[58:59], s[2:3], v102, s10, 0
	v_lshlrev_b32_e32 v60, 16, v106
	v_and_b32_e32 v61, 0xffff0000, v106
	v_lshlrev_b32_e32 v62, 16, v105
	v_and_b32_e32 v63, 0xffff0000, v105
	v_lshlrev_b32_e32 v78, 16, v104
	v_and_b32_e32 v79, 0xffff0000, v104
	v_lshlrev_b32_e32 v84, 16, v103
	v_and_b32_e32 v85, 0xffff0000, v103
	v_lshlrev_b32_e32 v86, 16, v110
	v_and_b32_e32 v87, 0xffff0000, v110
	v_lshlrev_b32_e32 v88, 16, v109
	v_and_b32_e32 v89, 0xffff0000, v109
	v_lshlrev_b32_e32 v90, 16, v108
	v_and_b32_e32 v91, 0xffff0000, v108
	v_lshlrev_b32_e32 v92, 16, v107
	v_and_b32_e32 v93, 0xffff0000, v107
	v_lshlrev_b32_e32 v96, 16, v113
	v_and_b32_e32 v97, 0xffff0000, v113
	v_lshlrev_b32_e32 v98, 16, v112
	v_and_b32_e32 v99, 0xffff0000, v112
	v_lshlrev_b32_e32 v100, 16, v111
	v_and_b32_e32 v101, 0xffff0000, v111
	v_mad_i64_i32 v[102:103], s[2:3], v115, s10, 0
	v_lshlrev_b32_e32 v104, 16, v119
	v_and_b32_e32 v105, 0xffff0000, v119
	v_lshlrev_b32_e32 v106, 16, v118
	v_and_b32_e32 v107, 0xffff0000, v118
	v_lshlrev_b32_e32 v108, 16, v117
	v_and_b32_e32 v109, 0xffff0000, v117
	v_lshlrev_b32_e32 v110, 16, v116
	v_and_b32_e32 v111, 0xffff0000, v116
; __device__ __forceinline__ unsigned pkbf(float lo, float hi) { typedef __bf16 bf2_t __attribute__((ext_vector_type(2))); f32x2 v = {lo, hi}; bf2_t b = __builtin_convertvector(v, bf2_t); return __builtin_bit_cast(unsigned, b); }
; __device__ __forceinline__ void phase_scan(const Args& a, unsigned char* ws, bf16* STB, int l, int vcu, int G, int tid, int z) {
;     ...
;         for (int i = 0; i < 16; ++i) {
;             const int n = dir ? 15 - i : i;
;             u32x4 w; w.x = pkbf(c[0], c[1]); w.y = pkbf(c[2], c[3]); w.z = pkbf(c[4], c[5]); w.w = pkbf(c[6], c[7]);
;             *(u32x4*)(base + (size_t)n * cst) = w;
; #pragma unroll
;             for (int e = 0; e < 4; ++e) { c[2 * e] = bflo(kv[n][e]) + g * c[2 * e]; c[2 * e + 1] = bfhi(kv[n][e]) + g * c[2 * e + 1]; }
	v_mad_i64_i32 v[112:113], s[2:3], v120, s10, 0
	v_lshlrev_b32_e32 v116, 16, v123
	v_and_b32_e32 v117, 0xffff0000, v123
	v_lshlrev_b32_e32 v118, 16, v122
	v_and_b32_e32 v119, 0xffff0000, v122
	v_mad_i64_i32 v[122:123], s[2:3], v125, s10, 0
	v_mad_i64_i32 v[132:133], s[2:3], v132, s10, 0
	v_mad_i64_i32 v[142:143], s[2:3], v142, s10, 0
	v_mad_i64_i32 v[152:153], s[2:3], v152, s10, 0
	v_mad_i64_i32 v[162:163], s[2:3], v162, s10, 0
	v_lshl_add_u64 v[8:9], v[8:9], 1, v[72:73]
	v_lshl_add_u64 v[18:19], v[18:19], 1, v[72:73]
	v_lshl_add_u64 v[28:29], v[28:29], 1, v[72:73]
	v_lshl_add_u64 v[38:39], v[38:39], 1, v[72:73]
	v_lshl_add_u64 v[48:49], v[48:49], 1, v[72:73]
	v_lshl_add_u64 v[58:59], v[58:59], 1, v[72:73]
	v_lshl_add_u64 v[102:103], v[102:103], 1, v[72:73]
	v_lshl_add_u64 v[112:113], v[112:113], 1, v[72:73]
	v_lshl_add_u64 v[122:123], v[122:123], 1, v[72:73]
	v_lshl_add_u64 v[132:133], v[132:133], 1, v[72:73]
	v_lshl_add_u64 v[142:143], v[142:143], 1, v[72:73]
	v_lshl_add_u64 v[152:153], v[152:153], 1, v[72:73]
	v_lshl_add_u64 v[72:73], v[162:163], 1, v[72:73]
	v_mul_f32_e32 v162, 0, v64
	v_lshlrev_b32_e32 v10, 16, v67
	v_and_b32_e32 v11, 0xffff0000, v67
	v_pk_add_f32 v[164:165], v[162:163], v[0:1] op_sel_hi:[0,1]
	v_pk_add_f32 v[166:167], v[162:163], v[2:3] op_sel_hi:[0,1]
	v_pk_add_f32 v[4:5], v[162:163], v[4:5] op_sel_hi:[0,1]
	v_pk_add_f32 v[6:7], v[162:163], v[6:7] op_sel_hi:[0,1]
	v_cvt_pk_bf16_f32 v0, v164, v165
	v_cvt_pk_bf16_f32 v1, v166, v167
	v_cvt_pk_bf16_f32 v2, v4, v5
	v_cvt_pk_bf16_f32 v3, v6, v7
	v_pk_fma_f32 v[10:11], v[64:65], v[164:165], v[10:11] op_sel_hi:[0,1,1]
	v_pk_fma_f32 v[12:13], v[64:65], v[166:167], v[12:13] op_sel_hi:[0,1,1]
	v_pk_fma_f32 v[4:5], v[64:65], v[4:5], v[14:15] op_sel_hi:[0,1,1]
	v_pk_fma_f32 v[6:7], v[64:65], v[6:7], v[16:17] op_sel_hi:[0,1,1]
	global_store_dwordx4 v[8:9], v[0:3], off
	v_pk_fma_f32 v[8:9], v[64:65], v[10:11], v[20:21] op_sel_hi:[0,1,1]
	v_lshlrev_b32_e32 v42, 16, v95
	v_cvt_pk_bf16_f32 v0, v10, v11
	v_cvt_pk_bf16_f32 v1, v12, v13
	v_cvt_pk_bf16_f32 v2, v4, v5
	v_cvt_pk_bf16_f32 v3, v6, v7
	v_pk_fma_f32 v[10:11], v[64:65], v[12:13], v[22:23] op_sel_hi:[0,1,1]
	v_pk_fma_f32 v[4:5], v[64:65], v[4:5], v[24:25] op_sel_hi:[0,1,1]
	v_pk_fma_f32 v[6:7], v[64:65], v[6:7], v[26:27] op_sel_hi:[0,1,1]
	v_and_b32_e32 v43, 0xffff0000, v95
	v_lshlrev_b32_e32 v44, 16, v94
	v_and_b32_e32 v45, 0xffff0000, v94
	global_store_dwordx4 v[18:19], v[0:3], off
	v_lshlrev_b32_e32 v94, 16, v114
	v_and_b32_e32 v95, 0xffff0000, v114
	v_cvt_pk_bf16_f32 v0, v8, v9
	v_cvt_pk_bf16_f32 v1, v10, v11
	v_cvt_pk_bf16_f32 v2, v4, v5
	v_cvt_pk_bf16_f32 v3, v6, v7
	v_pk_fma_f32 v[8:9], v[64:65], v[8:9], v[30:31] op_sel_hi:[0,1,1]
	v_pk_fma_f32 v[10:11], v[64:65], v[10:11], v[32:33] op_sel_hi:[0,1,1]
	v_pk_fma_f32 v[4:5], v[64:65], v[4:5], v[34:35] op_sel_hi:[0,1,1]
	v_pk_fma_f32 v[6:7], v[64:65], v[6:7], v[36:37] op_sel_hi:[0,1,1]
	global_store_dwordx4 v[28:29], v[0:3], off
	v_lshlrev_b32_e32 v114, 16, v124
	v_and_b32_e32 v115, 0xffff0000, v124
	v_cvt_pk_bf16_f32 v0, v8, v9
	v_cvt_pk_bf16_f32 v1, v10, v11
	v_cvt_pk_bf16_f32 v2, v4, v5
	v_cvt_pk_bf16_f32 v3, v6, v7
	v_pk_fma_f32 v[8:9], v[64:65], v[8:9], v[40:41] op_sel_hi:[0,1,1]
	v_pk_fma_f32 v[10:11], v[64:65], v[10:11], v[42:43] op_sel_hi:[0,1,1]
	v_pk_fma_f32 v[4:5], v[64:65], v[4:5], v[44:45] op_sel_hi:[0,1,1]
	v_pk_fma_f32 v[6:7], v[64:65], v[6:7], v[46:47] op_sel_hi:[0,1,1]
	global_store_dwordx4 v[38:39], v[0:3], off
	v_lshlrev_b32_e32 v120, 16, v121
	v_and_b32_e32 v121, 0xffff0000, v121
	v_cvt_pk_bf16_f32 v0, v8, v9
	v_cvt_pk_bf16_f32 v1, v10, v11
	v_cvt_pk_bf16_f32 v2, v4, v5
	v_cvt_pk_bf16_f32 v3, v6, v7
	v_pk_fma_f32 v[8:9], v[64:65], v[8:9], v[50:51] op_sel_hi:[0,1,1]
	v_pk_fma_f32 v[10:11], v[64:65], v[10:11], v[52:53] op_sel_hi:[0,1,1]
	v_pk_fma_f32 v[4:5], v[64:65], v[4:5], v[54:55] op_sel_hi:[0,1,1]
	v_pk_fma_f32 v[6:7], v[64:65], v[6:7], v[56:57] op_sel_hi:[0,1,1]
	global_store_dwordx4 v[48:49], v[0:3], off
	v_lshlrev_b32_e32 v124, 16, v126
	v_and_b32_e32 v125, 0xffff0000, v126
	v_cvt_pk_bf16_f32 v0, v8, v9
	v_cvt_pk_bf16_f32 v1, v10, v11
	v_cvt_pk_bf16_f32 v2, v4, v5
	v_cvt_pk_bf16_f32 v3, v6, v7
	v_pk_fma_f32 v[8:9], v[64:65], v[8:9], v[60:61] op_sel_hi:[0,1,1]
	v_pk_fma_f32 v[10:11], v[64:65], v[10:11], v[62:63] op_sel_hi:[0,1,1]
	v_pk_fma_f32 v[4:5], v[64:65], v[4:5], v[78:79] op_sel_hi:[0,1,1]
	v_pk_fma_f32 v[6:7], v[64:65], v[6:7], v[84:85] op_sel_hi:[0,1,1]
	global_store_dwordx4 v[58:59], v[0:3], off
	v_lshlrev_b32_e32 v126, 16, v127
	v_and_b32_e32 v127, 0xffff0000, v127
	v_cvt_pk_bf16_f32 v0, v8, v9
	v_cvt_pk_bf16_f32 v1, v10, v11
	v_cvt_pk_bf16_f32 v2, v4, v5
	v_cvt_pk_bf16_f32 v3, v6, v7
; __device__ __forceinline__ unsigned pkbf(float lo, float hi) { typedef __bf16 bf2_t __attribute__((ext_vector_type(2))); f32x2 v = {lo, hi}; bf2_t b = __builtin_convertvector(v, bf2_t); return __builtin_bit_cast(unsigned, b); }
; __device__ __forceinline__ void phase_scan(const Args& a, unsigned char* ws, bf16* STB, int l, int vcu, int G, int tid, int z) {
;     ...
;         for (int i = 0; i < 16; ++i) {
;             const int n = dir ? 15 - i : i;
;             u32x4 w; w.x = pkbf(c[0], c[1]); w.y = pkbf(c[2], c[3]); w.z = pkbf(c[4], c[5]); w.w = pkbf(c[6], c[7]);
;             *(u32x4*)(base + (size_t)n * cst) = w;
; #pragma unroll
;             for (int e = 0; e < 4; ++e) { c[2 * e] = bflo(kv[n][e]) + g * c[2 * e]; c[2 * e + 1] = bfhi(kv[n][e]) + g * c[2 * e + 1]; }
;         }
;     }
	v_pk_fma_f32 v[8:9], v[64:65], v[8:9], v[86:87] op_sel_hi:[0,1,1]
	v_pk_fma_f32 v[10:11], v[64:65], v[10:11], v[88:89] op_sel_hi:[0,1,1]
	v_pk_fma_f32 v[4:5], v[64:65], v[4:5], v[90:91] op_sel_hi:[0,1,1]
	v_pk_fma_f32 v[6:7], v[64:65], v[6:7], v[92:93] op_sel_hi:[0,1,1]
	global_store_dwordx4 v[70:71], v[0:3], off
	v_lshlrev_b32_e32 v128, 16, v129
	v_and_b32_e32 v129, 0xffff0000, v129
	v_cvt_pk_bf16_f32 v0, v8, v9
	v_cvt_pk_bf16_f32 v1, v10, v11
	v_cvt_pk_bf16_f32 v2, v4, v5
	v_cvt_pk_bf16_f32 v3, v6, v7
	v_pk_fma_f32 v[8:9], v[64:65], v[8:9], v[94:95] op_sel_hi:[0,1,1]
	v_pk_fma_f32 v[10:11], v[64:65], v[10:11], v[96:97] op_sel_hi:[0,1,1]
	v_pk_fma_f32 v[4:5], v[64:65], v[4:5], v[98:99] op_sel_hi:[0,1,1]
	v_pk_fma_f32 v[6:7], v[64:65], v[6:7], v[100:101] op_sel_hi:[0,1,1]
	global_store_dwordx4 v[68:69], v[0:3], off
	v_lshlrev_b32_e32 v130, 16, v131
	v_and_b32_e32 v131, 0xffff0000, v131
	v_cvt_pk_bf16_f32 v0, v8, v9
	v_cvt_pk_bf16_f32 v1, v10, v11
	v_cvt_pk_bf16_f32 v2, v4, v5
	v_cvt_pk_bf16_f32 v3, v6, v7
	v_pk_fma_f32 v[8:9], v[64:65], v[8:9], v[104:105] op_sel_hi:[0,1,1]
	v_pk_fma_f32 v[10:11], v[64:65], v[10:11], v[106:107] op_sel_hi:[0,1,1]
	v_pk_fma_f32 v[4:5], v[64:65], v[4:5], v[108:109] op_sel_hi:[0,1,1]
	v_pk_fma_f32 v[6:7], v[64:65], v[6:7], v[110:111] op_sel_hi:[0,1,1]
	global_store_dwordx4 v[102:103], v[0:3], off
	v_lshlrev_b32_e32 v134, 16, v135
	v_and_b32_e32 v135, 0xffff0000, v135
	v_cvt_pk_bf16_f32 v0, v8, v9
	v_cvt_pk_bf16_f32 v1, v10, v11
	v_cvt_pk_bf16_f32 v2, v4, v5
	v_cvt_pk_bf16_f32 v3, v6, v7
	v_pk_fma_f32 v[8:9], v[64:65], v[8:9], v[114:115] op_sel_hi:[0,1,1]
	v_pk_fma_f32 v[10:11], v[64:65], v[10:11], v[116:117] op_sel_hi:[0,1,1]
	v_pk_fma_f32 v[4:5], v[64:65], v[4:5], v[118:119] op_sel_hi:[0,1,1]
	v_pk_fma_f32 v[6:7], v[64:65], v[6:7], v[120:121] op_sel_hi:[0,1,1]
	v_lshlrev_b32_e32 v136, 16, v137
	v_and_b32_e32 v137, 0xffff0000, v137
	v_lshlrev_b32_e32 v138, 16, v139
	v_and_b32_e32 v139, 0xffff0000, v139
	v_lshlrev_b32_e32 v140, 16, v141
	v_and_b32_e32 v141, 0xffff0000, v141
	global_store_dwordx4 v[112:113], v[0:3], off
	v_lshlrev_b32_e32 v144, 16, v145
	v_and_b32_e32 v145, 0xffff0000, v145
	v_cvt_pk_bf16_f32 v0, v8, v9
	v_cvt_pk_bf16_f32 v1, v10, v11
	v_cvt_pk_bf16_f32 v2, v4, v5
	v_cvt_pk_bf16_f32 v3, v6, v7
	v_pk_fma_f32 v[8:9], v[64:65], v[8:9], v[124:125] op_sel_hi:[0,1,1]
	v_pk_fma_f32 v[10:11], v[64:65], v[10:11], v[126:127] op_sel_hi:[0,1,1]
	v_pk_fma_f32 v[4:5], v[64:65], v[4:5], v[128:129] op_sel_hi:[0,1,1]
	v_pk_fma_f32 v[6:7], v[64:65], v[6:7], v[130:131] op_sel_hi:[0,1,1]
	v_lshlrev_b32_e32 v146, 16, v147
	v_and_b32_e32 v147, 0xffff0000, v147
	v_lshlrev_b32_e32 v148, 16, v149
	v_and_b32_e32 v149, 0xffff0000, v149
	v_lshlrev_b32_e32 v150, 16, v151
	v_and_b32_e32 v151, 0xffff0000, v151
	global_store_dwordx4 v[122:123], v[0:3], off
	v_lshlrev_b32_e32 v154, 16, v155
	v_and_b32_e32 v155, 0xffff0000, v155
	v_cvt_pk_bf16_f32 v0, v8, v9
	v_cvt_pk_bf16_f32 v1, v10, v11
	v_cvt_pk_bf16_f32 v2, v4, v5
	v_cvt_pk_bf16_f32 v3, v6, v7
	v_pk_fma_f32 v[8:9], v[64:65], v[8:9], v[134:135] op_sel_hi:[0,1,1]
	v_pk_fma_f32 v[10:11], v[64:65], v[10:11], v[136:137] op_sel_hi:[0,1,1]
	v_pk_fma_f32 v[4:5], v[64:65], v[4:5], v[138:139] op_sel_hi:[0,1,1]
	v_pk_fma_f32 v[6:7], v[64:65], v[6:7], v[140:141] op_sel_hi:[0,1,1]
	v_lshlrev_b32_e32 v156, 16, v157
	v_and_b32_e32 v157, 0xffff0000, v157
	v_lshlrev_b32_e32 v158, 16, v159
	v_and_b32_e32 v159, 0xffff0000, v159
	v_lshlrev_b32_e32 v160, 16, v161
	v_and_b32_e32 v161, 0xffff0000, v161
	global_store_dwordx4 v[132:133], v[0:3], off
	s_nop 1
	v_cvt_pk_bf16_f32 v0, v8, v9
	v_cvt_pk_bf16_f32 v1, v10, v11
	v_cvt_pk_bf16_f32 v2, v4, v5
	v_cvt_pk_bf16_f32 v3, v6, v7
	v_pk_fma_f32 v[8:9], v[64:65], v[8:9], v[144:145] op_sel_hi:[0,1,1]
	v_pk_fma_f32 v[10:11], v[64:65], v[10:11], v[146:147] op_sel_hi:[0,1,1]
	v_pk_fma_f32 v[4:5], v[64:65], v[4:5], v[148:149] op_sel_hi:[0,1,1]
	v_pk_fma_f32 v[6:7], v[64:65], v[6:7], v[150:151] op_sel_hi:[0,1,1]
	global_store_dwordx4 v[142:143], v[0:3], off
	s_nop 1
	v_cvt_pk_bf16_f32 v0, v8, v9
	v_cvt_pk_bf16_f32 v1, v10, v11
	v_cvt_pk_bf16_f32 v2, v4, v5
	v_cvt_pk_bf16_f32 v3, v6, v7
	v_pk_fma_f32 v[8:9], v[64:65], v[8:9], v[154:155] op_sel_hi:[0,1,1]
	v_pk_fma_f32 v[10:11], v[64:65], v[10:11], v[156:157] op_sel_hi:[0,1,1]
	v_pk_fma_f32 v[4:5], v[64:65], v[4:5], v[158:159] op_sel_hi:[0,1,1]
	v_pk_fma_f32 v[6:7], v[64:65], v[6:7], v[160:161] op_sel_hi:[0,1,1]
	global_store_dwordx4 v[152:153], v[0:3], off
	s_nop 1
	v_cvt_pk_bf16_f32 v0, v8, v9
	v_cvt_pk_bf16_f32 v1, v10, v11
	v_cvt_pk_bf16_f32 v2, v4, v5
	v_cvt_pk_bf16_f32 v3, v6, v7
	global_store_dwordx4 v[72:73], v[0:3], off
	s_andn2_b64 exec, exec, s[14:15]
	s_cbranch_execnz .LBB0_564

; __device__ __forceinline__ void ret_gammas(const Args& a, int l, int h, float& lgf2, float& lgb2) {
;     const float xf = a.in[8][(l * 2 + 0) * 4 + h], xb = a.in[8][(l * 2 + 1) * 4 + h];
;     lgf2 = -log1pf(expf(-xf)) * LOG2E; lgb2 = -log1pf(expf(-xb)) * LOG2E;
; }
; __device__ __forceinline__ void phase_scan(const Args& a, unsigned char* ws, bf16* STB, int l, int vcu, int G, int tid, int z) {
;     bf16* ST = STB;
;     const int gt = vcu * 512 + tid, NT = G * 512;
;     for (int it = gt; it < 192 * 2 * 2048; it += NT) {
;         const int grp = it & 2047, dir = (it >> 11) & 1, bh = it >> 12, h = bh & 3;
;         float lgf2, lgb2; ret_gammas(a, l, h, lgf2, lgb2);
;         const float g = __builtin_amdgcn_exp2f(128.f * (dir ? lgb2 : lgf2));
;         bf16* base = ST + ((size_t)(bh * 16) * 2 + dir) * 16384 + grp * 8;
;         u32x4 kv[16];
;         const size_t cst = (size_t)(32768 + z);
; #pragma unroll
;         for (int n = 0; n < 16; ++n) kv[n] = *(const u32x4*)(base + (size_t)n * cst);
.LBB0_1292:
	v_ashrrev_i32_e32 v1, 12, v74
	v_lshlrev_b32_e32 v3, 2, v1
	v_and_b32_e32 v3, 12, v3
	global_load_dword v67, v3, s[6:7] offset:32
	global_load_dword v79, v3, s[6:7] offset:48
	v_lshlrev_b32_e32 v4, 4, v1
	v_ashrrev_i32_e32 v5, 31, v4
	v_bfe_u32 v78, v74, 11, 1
	v_lshlrev_b64 v[4:5], 16, v[4:5]
	v_and_b32_e32 v2, 0x3ff8, v75
	v_lshlrev_b32_e32 v0, 15, v78
	v_lshl_add_u64 v[4:5], s[8:9], 0, v[4:5]
	v_lshl_add_u32 v0, v2, 1, v0
	v_add_co_u32_e32 v72, vcc, v4, v0
	v_addc_co_u32_e32 v73, vcc, 0, v5, vcc
	v_lshl_add_u64 v[4:5], s[10:11], 1, v[72:73]
	v_lshl_add_u64 v[12:13], v[4:5], 0, s[12:13]
	v_bfe_i32 v0, v74, 11, 1
	v_lshl_add_u64 v[14:15], v[12:13], 0, s[12:13]
	v_and_b32_e32 v0, 15, v0
	v_add_u32_e32 v6, 7, v78
	v_sub_u32_e32 v8, 8, v78
	v_lshl_add_u64 v[16:17], v[14:15], 0, s[12:13]
	v_mad_i64_i32 v[0:1], s[2:3], v0, s10, 0
	v_mad_i64_i32 v[6:7], s[2:3], v6, s10, 0
	v_mad_i64_i32 v[8:9], s[2:3], v8, s10, 0
	v_lshl_add_u64 v[18:19], v[16:17], 0, s[12:13]
	v_lshl_add_u64 v[84:85], v[0:1], 1, v[72:73]
	v_lshl_add_u64 v[70:71], v[6:7], 1, v[72:73]
	v_lshl_add_u64 v[68:69], v[8:9], 1, v[72:73]
	global_load_dwordx4 v[56:59], v[72:73], off
	global_load_dwordx4 v[0:3], v[4:5], off
	s_nop 0
	global_load_dwordx4 v[4:7], v[12:13], off
	global_load_dwordx4 v[8:11], v[14:15], off
	s_nop 0
	global_load_dwordx4 v[12:15], v[16:17], off
	global_load_dwordx4 v[20:23], v[18:19], off
	v_lshl_add_u64 v[16:17], v[18:19], 0, s[12:13]
	global_load_dwordx4 v[32:35], v[16:17], off
	v_lshl_add_u64 v[16:17], v[16:17], 0, s[12:13]
	global_load_dwordx4 v[48:51], v[16:17], off
	v_lshl_add_u64 v[16:17], v[16:17], 0, s[12:13]
	global_load_dwordx4 v[52:55], v[16:17], off
	v_lshl_add_u64 v[16:17], v[16:17], 0, s[12:13]
	global_load_dwordx4 v[44:47], v[16:17], off
	v_lshl_add_u64 v[16:17], v[16:17], 0, s[12:13]
	global_load_dwordx4 v[40:43], v[16:17], off
	v_lshl_add_u64 v[16:17], v[16:17], 0, s[12:13]
	global_load_dwordx4 v[36:39], v[16:17], off
	v_lshl_add_u64 v[16:17], v[16:17], 0, s[12:13]
	global_load_dwordx4 v[28:31], v[16:17], off
	v_lshl_add_u64 v[16:17], v[16:17], 0, s[12:13]
	v_lshl_add_u64 v[60:61], v[16:17], 0, s[12:13]
	global_load_dwordx4 v[24:27], v[16:17], off
	v_add_u32_e32 v74, s0, v74
	global_load_dwordx4 v[16:19], v[60:61], off
	v_lshl_add_u64 v[60:61], v[60:61], 0, s[12:13]
	global_load_dwordx4 v[60:63], v[60:61], off
	v_cmp_lt_i32_e32 vcc, s23, v74
	global_store_dwordx4 v[84:85], v[80:83], off
	s_or_b64 s[14:15], vcc, s[14:15]
	v_add_u32_e32 v75, s1, v75
	s_cmp_eq_u32 s98, 0
	s_cbranch_scc1 .Lscan_gskip_1
	s_waitcnt vmcnt(17)
	v_mul_f32_e32 v64, 0xbfb8aa3b, v67
	v_mul_f32_e32 v84, 0xbfb8aa3b, v79
	v_fma_f32 v85, v67, s16, -v64
	v_rndne_f32_e32 v86, v64
	v_fma_f32 v87, v79, s16, -v84
	v_rndne_f32_e32 v88, v84
	v_fmac_f32_e32 v85, 0xb2a5705f, v67
	v_sub_f32_e32 v64, v64, v86
	v_fmac_f32_e32 v87, 0xb2a5705f, v79
	v_sub_f32_e32 v84, v84, v88
	v_add_f32_e32 v64, v64, v85
	v_cvt_i32_f32_e32 v86, v86
	v_add_f32_e32 v84, v84, v87
	v_exp_f32_e32 v64, v64
	v_cvt_i32_f32_e32 v88, v88
	v_exp_f32_e32 v84, v84
	v_cmp_nlt_f32_e64 s[2:3], s17, v67
	v_ldexp_f32 v64, v64, v86
	v_cmp_nlt_f32_e32 vcc, s17, v79
	v_ldexp_f32 v84, v84, v88
	v_cndmask_b32_e64 v64, 0, v64, s[2:3]
	v_cmp_ngt_f32_e64 s[2:3], s18, v67
	v_cndmask_b32_e32 v84, 0, v84, vcc
	v_cmp_ngt_f32_e32 vcc, s18, v79
	v_cndmask_b32_e64 v64, v76, v64, s[2:3]
	v_add_f32_e32 v67, 1.0, v64
	v_cndmask_b32_e32 v79, v76, v84, vcc
	v_add_f32_e32 v88, 1.0, v79
	v_add_f32_e32 v89, -1.0, v67
	v_frexp_mant_f32_e32 v90, v67
	v_cvt_f64_f32_e32 v[84:85], v67
	v_add_f32_e32 v91, -1.0, v88
	v_frexp_mant_f32_e32 v92, v88
	v_cvt_f64_f32_e32 v[86:87], v88
	v_sub_f32_e32 v93, v89, v67
	v_frexp_exp_i32_f64_e32 v84, v[84:85]
	v_cmp_gt_f32_e32 vcc, s20, v90
	v_sub_f32_e32 v89, v64, v89
	v_sub_f32_e32 v85, v91, v88
	v_frexp_exp_i32_f64_e32 v86, v[86:87]
	v_cmp_gt_f32_e64 s[2:3], s20, v92
	v_add_f32_e32 v87, 1.0, v93
	v_subbrev_co_u32_e32 v84, vcc, 0, v84, vcc
	v_sub_f32_e32 v90, v79, v91
	v_add_f32_e32 v85, 1.0, v85
	v_subbrev_co_u32_e64 v86, vcc, 0, v86, s[2:3]
	v_add_f32_e32 v87, v89, v87
	v_sub_u32_e32 v89, 0, v84
	v_add_f32_e32 v85, v90, v85
	v_sub_u32_e32 v90, 0, v86
	v_ldexp_f32 v67, v67, v89
	v_ldexp_f32 v88, v88, v90
	v_ldexp_f32 v85, v85, v90
	v_add_f32_e32 v90, -1.0, v67
	v_add_f32_e32 v92, 1.0, v67
	v_ldexp_f32 v87, v87, v89
	v_add_f32_e32 v93, -1.0, v88
	v_add_f32_e32 v94, 1.0, v88
	v_add_f32_e32 v89, 1.0, v90
	v_add_f32_e32 v91, -1.0, v92
	v_add_f32_e32 v95, 1.0, v93
	v_add_f32_e32 v96, -1.0, v94
	v_sub_f32_e32 v89, v67, v89
	v_sub_f32_e32 v67, v67, v91
	v_sub_f32_e32 v91, v88, v95
	v_sub_f32_e32 v88, v88, v96
	v_add_f32_e32 v67, v87, v67
	v_add_f32_e32 v95, v87, v89
	v_add_f32_e32 v87, v85, v91
	v_add_f32_e32 v85, v85, v88
	v_add_f32_e32 v100, v92, v67
	v_add_f32_e32 v101, v94, v85
	v_rcp_f32_e32 v102, v100
	v_rcp_f32_e32 v103, v101
	v_add_f32_e32 v89, v90, v95
	v_add_f32_e32 v91, v93, v87
	v_sub_f32_e32 v88, v92, v100
	v_sub_f32_e32 v92, v94, v101
	v_mul_f32_e32 v105, v89, v102
	v_add_f32_e32 v85, v85, v92
	v_mul_f32_e32 v106, v91, v103
	v_mul_f32_e32 v92, v100, v105
	v_add_f32_e32 v67, v67, v88
	v_mul_f32_e32 v94, v101, v106
	v_fma_f32 v96, v105, v100, -v92
	v_fma_f32 v98, v106, v101, -v94
	v_fmac_f32_e32 v96, v105, v67
	v_sub_f32_e32 v90, v90, v89
	v_sub_f32_e32 v93, v93, v91
	v_fmac_f32_e32 v98, v106, v85
	v_add_f32_e32 v88, v92, v96
	v_add_f32_e32 v104, v95, v90
	v_add_f32_e32 v87, v87, v93
	v_add_f32_e32 v90, v94, v98
	v_sub_f32_e32 v93, v89, v88
	v_mov_b32_e32 v97, v88
	v_sub_f32_e32 v95, v91, v90
	v_pk_add_f32 v[88:89], v[88:89], v[92:93] neg_lo:[0,1] neg_hi:[0,1]
	v_mov_b32_e32 v99, v90
; __device__ __forceinline__ void ret_gammas(const Args& a, int l, int h, float& lgf2, float& lgb2) {
;     const float xf = a.in[8][(l * 2 + 0) * 4 + h], xb = a.in[8][(l * 2 + 1) * 4 + h];
;     lgf2 = -log1pf(expf(-xf)) * LOG2E; lgb2 = -log1pf(expf(-xb)) * LOG2E;
; __device__ __forceinline__ void phase_scan(const Args& a, unsigned char* ws, bf16* STB, int l, int vcu, int G, int tid, int z) {
;     ...
;         const float g = __builtin_amdgcn_exp2f(128.f * (dir ? lgb2 : lgf2));
	v_pk_add_f32 v[90:91], v[90:91], v[94:95] neg_lo:[0,1] neg_hi:[0,1]
	v_pk_add_f32 v[88:89], v[88:89], v[96:97] neg_lo:[0,1] neg_hi:[0,1]
	v_pk_add_f32 v[90:91], v[90:91], v[98:99] neg_lo:[0,1] neg_hi:[0,1]
	v_add_f32_e32 v89, v104, v89
	v_add_f32_e32 v87, v87, v91
	v_add_f32_e32 v88, v88, v89
	v_add_f32_e32 v87, v90, v87
	v_add_f32_e32 v89, v93, v88
	v_add_f32_e32 v91, v95, v87
	v_mul_f32_e32 v90, v102, v89
	v_mul_f32_e32 v97, v103, v91
	v_mul_f32_e32 v92, v100, v90
	v_sub_f32_e32 v93, v93, v89
	v_add_f32_e32 v107, v105, v90
	v_mul_f32_e32 v94, v101, v97
	v_fma_f32 v96, v90, v100, -v92
	v_add_f32_e32 v104, v88, v93
	v_add_f32_e32 v108, v106, v97
	v_sub_f32_e32 v88, v107, v105
	v_fma_f32 v98, v97, v101, -v94
	v_fmac_f32_e32 v96, v90, v67
	v_sub_f32_e32 v93, v108, v106
	v_sub_f32_e32 v67, v90, v88
	v_fmac_f32_e32 v98, v97, v85
	v_add_f32_e32 v88, v92, v96
	v_sub_f32_e32 v95, v95, v91
	v_sub_f32_e32 v85, v97, v93
	v_add_f32_e32 v90, v94, v98
	v_sub_f32_e32 v93, v89, v88
	v_add_f32_e32 v87, v87, v95
	v_mov_b32_e32 v97, v88
	v_sub_f32_e32 v95, v91, v90
	v_pk_add_f32 v[88:89], v[88:89], v[92:93] neg_lo:[0,1] neg_hi:[0,1]
	v_mov_b32_e32 v99, v90
	v_pk_add_f32 v[90:91], v[90:91], v[94:95] neg_lo:[0,1] neg_hi:[0,1]
	v_pk_add_f32 v[88:89], v[88:89], v[96:97] neg_lo:[0,1] neg_hi:[0,1]
	v_pk_add_f32 v[90:91], v[90:91], v[98:99] neg_lo:[0,1] neg_hi:[0,1]
	v_add_f32_e32 v89, v104, v89
	v_add_f32_e32 v87, v87, v91
	v_add_f32_e32 v88, v88, v89
	v_add_f32_e32 v87, v90, v87
	v_add_f32_e32 v88, v93, v88
	v_add_f32_e32 v87, v95, v87
	v_mul_f32_e32 v88, v102, v88
	v_mul_f32_e32 v87, v103, v87
	v_add_f32_e32 v67, v67, v88
	v_cvt_f32_i32_e32 v84, v84
	v_add_f32_e32 v87, v85, v87
	v_add_f32_e32 v85, v107, v67
	v_cvt_f32_i32_e32 v86, v86
	v_add_f32_e32 v88, v108, v87
	v_mul_f32_e32 v90, v85, v85
	v_sub_f32_e32 v92, v85, v107
	v_mul_f32_e32 v94, v88, v88
	v_sub_f32_e32 v93, v88, v108
	v_fmamk_f32 v95, v90, 0x3e9b6dac, v77
	v_ldexp_f32 v89, v85, 1
	v_sub_f32_e32 v92, v67, v92
	v_mul_f32_e32 v85, v85, v90
	v_fmamk_f32 v96, v94, 0x3e9b6dac, v77
	v_sub_f32_e32 v93, v87, v93
	v_fmaak_f32 v67, v90, v95, 0x3f2aaada
	v_mul_f32_e32 v87, v88, v94
	v_ldexp_f32 v95, v92, 1
	v_ldexp_f32 v104, v93, 1
	v_pk_mul_f32 v[92:93], v[84:85], v[66:67]
	v_fmaak_f32 v67, v94, v96, 0x3f2aaada
	v_ldexp_f32 v91, v88, 1
	v_fma_f32 v88, v84, s21, -v92
	v_pk_mul_f32 v[96:97], v[86:87], v[66:67]
	v_fmac_f32_e32 v88, 0xb102e308, v84
	v_fma_f32 v90, v86, s21, -v96
	v_pk_add_f32 v[98:99], v[92:93], v[88:89]
	v_fmac_f32_e32 v90, 0xb102e308, v86
	v_sub_f32_e32 v67, v99, v89
	v_pk_add_f32 v[102:103], v[96:97], v[90:91]
	v_sub_f32_e32 v67, v93, v67
	v_sub_f32_e32 v85, v103, v91
	v_mov_b32_e32 v94, v92
	v_add_f32_e32 v95, v95, v67
	v_sub_f32_e32 v67, v97, v85
	v_mov_b32_e32 v84, v96
	v_pk_add_f32 v[86:87], v[98:99], v[92:93] neg_lo:[0,1] neg_hi:[0,1]
	v_pk_add_f32 v[92:93], v[102:103], v[96:97] neg_lo:[0,1] neg_hi:[0,1]
	v_pk_add_f32 v[96:97], v[98:99], v[94:95]
	v_add_f32_e32 v85, v104, v67
	v_mov_b32_e32 v89, v98
	v_mov_b32_e32 v87, v97
	v_pk_add_f32 v[106:107], v[102:103], v[84:85]
	v_mov_b32_e32 v91, v102
	v_mov_b32_e32 v104, v85
	v_pk_add_f32 v[84:85], v[88:89], v[86:87] neg_lo:[0,1] neg_hi:[0,1]
	v_pk_add_f32 v[86:87], v[88:89], v[86:87]
	v_mov_b32_e32 v93, v107
	v_pk_add_f32 v[108:109], v[86:87], v[98:99] op_sel:[1,0] op_sel_hi:[0,1] neg_lo:[0,1] neg_hi:[0,1]
	v_pk_add_f32 v[110:111], v[90:91], v[92:93] neg_lo:[0,1] neg_hi:[0,1]
	v_pk_add_f32 v[90:91], v[90:91], v[92:93]
	v_mov_b32_e32 v101, v98
	v_mov_b32_e32 v100, v95
	v_mov_b32_e32 v94, v97
	v_mov_b32_e32 v95, v87
	v_pk_add_f32 v[92:93], v[96:97], v[108:109] op_sel_hi:[1,0] neg_lo:[0,1] neg_hi:[0,1]
	v_pk_mov_b32 v[96:97], v[98:99], v[108:109] op_sel:[1,0]
	v_pk_add_f32 v[98:99], v[90:91], v[102:103] op_sel:[1,0] op_sel_hi:[0,1] neg_lo:[0,1] neg_hi:[0,1]
	v_mov_b32_e32 v88, v107
	v_mov_b32_e32 v89, v91
	v_pk_add_f32 v[94:95], v[94:95], v[96:97] neg_lo:[0,1] neg_hi:[0,1]
	v_pk_add_f32 v[96:97], v[106:107], v[98:99] op_sel_hi:[1,0] neg_lo:[0,1] neg_hi:[0,1]
	v_pk_mov_b32 v[98:99], v[102:103], v[98:99] op_sel:[1,0]
	v_mov_b32_e32 v105, v102
	v_mov_b32_e32 v92, v84
	v_pk_add_f32 v[94:95], v[100:101], v[94:95] neg_lo:[0,1] neg_hi:[0,1]
	v_pk_add_f32 v[88:89], v[88:89], v[98:99] neg_lo:[0,1] neg_hi:[0,1]
	v_mov_b32_e32 v96, v110
	v_pk_add_f32 v[92:93], v[92:93], v[94:95]
	v_pk_add_f32 v[88:89], v[104:105], v[88:89] neg_lo:[0,1] neg_hi:[0,1]
	v_pk_add_f32 v[98:99], v[92:93], v[92:93] op_sel:[0,1] op_sel_hi:[1,0]
	v_pk_add_f32 v[96:97], v[96:97], v[88:89]
	v_mov_b32_e32 v85, v87
	v_pk_add_f32 v[86:87], v[86:87], v[98:99] op_sel:[1,0] op_sel_hi:[0,1]
	v_mov_b32_e32 v95, v98
	v_pk_add_f32 v[98:99], v[96:97], v[96:97] op_sel:[0,1] op_sel_hi:[1,0]
	v_mov_b32_e32 v111, v91
	v_mov_b32_e32 v93, v86
	v_pk_add_f32 v[90:91], v[90:91], v[98:99] op_sel:[1,0] op_sel_hi:[0,1]
	v_mov_b32_e32 v89, v98
	v_pk_add_f32 v[98:99], v[92:93], v[84:85] neg_lo:[0,1] neg_hi:[0,1]
	v_mov_b32_e32 v97, v90
	v_sub_f32_e32 v67, v92, v98
	v_pk_add_f32 v[92:93], v[96:97], v[110:111] neg_lo:[0,1] neg_hi:[0,1]
	v_pk_add_f32 v[94:95], v[94:95], v[98:99] neg_lo:[0,1] neg_hi:[0,1]
	v_sub_f32_e32 v67, v84, v67
	v_sub_f32_e32 v87, v96, v92
	v_pk_add_f32 v[84:85], v[88:89], v[92:93] neg_lo:[0,1] neg_hi:[0,1]
	v_add_f32_e32 v67, v94, v67
	v_sub_f32_e32 v87, v110, v87
	v_add_f32_e32 v67, v67, v95
	v_add_f32_e32 v84, v84, v87
	v_add_f32_e32 v67, v86, v67
	v_add_f32_e32 v84, v84, v85
	v_cmp_neq_f32_e32 vcc, s19, v64
	v_add_f32_e32 v84, v90, v84
	v_cmp_lt_f32_e64 s[2:3], |v64|, s22
	v_cndmask_b32_e32 v67, v76, v67, vcc
	v_cmp_neq_f32_e32 vcc, s19, v79
	v_cndmask_b32_e64 v64, v67, v64, s[2:3]
	s_nop 0
	v_cndmask_b32_e32 v67, v76, v84, vcc
	v_cmp_lt_f32_e64 vcc, |v79|, s22
	s_nop 1
	v_cndmask_b32_e32 v67, v67, v79, vcc
	v_cmp_eq_u32_e32 vcc, 0, v78
	s_nop 1
	v_cndmask_b32_e32 v64, v67, v64, vcc
	v_mul_f32_e32 v64, 0xbfb8aa3b, v64
	v_mul_f32_e32 v64, 0x43000000, v64
	v_exp_f32_e32 v64, v64
	s_mov_b32 s98, s99
